# stack26: stack25 + sample-NSA selected-branch PV: 4 per-head probability LDS reads per key row issued together (counted waits, same FMA order)
# baseline (speedup 1.0000x reference)
.LBB0_1565:
	s_or_b64 exec, exec, s[0:1]
	v_add_u32_e32 v132, 0, v124
	ds_read_b32 v82, v132
	v_cmp_gt_u32_e64 s[0:1], s22, v131
	s_waitcnt lgkmcnt(0)
	v_pk_fma_f32 v[68:69], v[36:37], v[82:83], v[68:69] op_sel_hi:[1,0,1]
	v_pk_fma_f32 v[66:67], v[34:35], v[82:83], v[66:67] op_sel_hi:[1,0,1]
	ds_read_b32 v82, v132 offset:4224
	s_waitcnt lgkmcnt(0)
	v_pk_fma_f32 v[80:81], v[36:37], v[82:83], v[80:81] op_sel_hi:[1,0,1]
	v_pk_fma_f32 v[78:79], v[34:35], v[82:83], v[78:79] op_sel_hi:[1,0,1]
	ds_read_b32 v82, v132 offset:8448
	s_waitcnt lgkmcnt(0)
	v_pk_fma_f32 v[76:77], v[36:37], v[82:83], v[76:77] op_sel_hi:[1,0,1]
	v_pk_fma_f32 v[74:75], v[34:35], v[82:83], v[74:75] op_sel_hi:[1,0,1]
	ds_read_b32 v82, v132 offset:12672
	s_waitcnt lgkmcnt(0)
	v_pk_fma_f32 v[72:73], v[36:37], v[82:83], v[72:73] op_sel_hi:[1,0,1]
	v_pk_fma_f32 v[70:71], v[34:35], v[82:83], v[70:71] op_sel_hi:[1,0,1]
	s_and_saveexec_b64 s[6:7], s[0:1]
	s_cbranch_execz .LBB0_1573
	ds_read_b32 v82, v132 offset:128
	ds_read_b32 v216, v132 offset:4352
	ds_read_b32 v218, v132 offset:8576
	ds_read_b32 v220, v132 offset:12800
	s_waitcnt vmcnt(6) lgkmcnt(3)
	v_pk_fma_f32 v[68:69], v[40:41], v[82:83], v[68:69] op_sel_hi:[1,0,1]
	v_pk_fma_f32 v[66:67], v[38:39], v[82:83], v[66:67] op_sel_hi:[1,0,1]
	s_waitcnt lgkmcnt(2)
	v_pk_fma_f32 v[80:81], v[40:41], v[216:217], v[80:81] op_sel_hi:[1,0,1]
	v_pk_fma_f32 v[78:79], v[38:39], v[216:217], v[78:79] op_sel_hi:[1,0,1]
	s_waitcnt lgkmcnt(1)
	v_pk_fma_f32 v[76:77], v[40:41], v[218:219], v[76:77] op_sel_hi:[1,0,1]
	v_pk_fma_f32 v[74:75], v[38:39], v[218:219], v[74:75] op_sel_hi:[1,0,1]
	s_waitcnt lgkmcnt(0)
	v_pk_fma_f32 v[72:73], v[40:41], v[220:221], v[72:73] op_sel_hi:[1,0,1]
	v_pk_fma_f32 v[70:71], v[38:39], v[220:221], v[70:71] op_sel_hi:[1,0,1]
	s_or_b64 exec, exec, s[6:7]
	v_cmp_gt_u32_e64 s[0:1], s26, v131
	s_and_saveexec_b64 s[6:7], s[0:1]
	s_cbranch_execnz .LBB0_1574

.LBB0_1568:
	ds_read_b32 v82, v132 offset:384
	ds_read_b32 v216, v132 offset:4608
	ds_read_b32 v218, v132 offset:8832
	ds_read_b32 v220, v132 offset:13056
	s_waitcnt vmcnt(4) lgkmcnt(3)
	v_pk_fma_f32 v[68:69], v[48:49], v[82:83], v[68:69] op_sel_hi:[1,0,1]
	v_pk_fma_f32 v[66:67], v[46:47], v[82:83], v[66:67] op_sel_hi:[1,0,1]
	s_waitcnt lgkmcnt(2)
	v_pk_fma_f32 v[80:81], v[48:49], v[216:217], v[80:81] op_sel_hi:[1,0,1]
	v_pk_fma_f32 v[78:79], v[46:47], v[216:217], v[78:79] op_sel_hi:[1,0,1]
	s_waitcnt lgkmcnt(1)
	v_pk_fma_f32 v[76:77], v[48:49], v[218:219], v[76:77] op_sel_hi:[1,0,1]
	v_pk_fma_f32 v[74:75], v[46:47], v[218:219], v[74:75] op_sel_hi:[1,0,1]
	s_waitcnt lgkmcnt(0)
	v_pk_fma_f32 v[72:73], v[48:49], v[220:221], v[72:73] op_sel_hi:[1,0,1]
	v_pk_fma_f32 v[70:71], v[46:47], v[220:221], v[70:71] op_sel_hi:[1,0,1]
	s_or_b64 exec, exec, s[6:7]
	v_cmp_gt_u32_e64 s[0:1], s16, v131
	s_and_saveexec_b64 s[6:7], s[0:1]
	s_cbranch_execnz .LBB0_1576

.LBB0_1570:
	ds_read_b32 v82, v132 offset:640
	ds_read_b32 v216, v132 offset:4864
	ds_read_b32 v218, v132 offset:9088
	ds_read_b32 v220, v132 offset:13312
	s_waitcnt vmcnt(2) lgkmcnt(3)
	v_pk_fma_f32 v[68:69], v[56:57], v[82:83], v[68:69] op_sel_hi:[1,0,1]
	v_pk_fma_f32 v[66:67], v[54:55], v[82:83], v[66:67] op_sel_hi:[1,0,1]
	s_waitcnt lgkmcnt(2)
	v_pk_fma_f32 v[80:81], v[56:57], v[216:217], v[80:81] op_sel_hi:[1,0,1]
	v_pk_fma_f32 v[78:79], v[54:55], v[216:217], v[78:79] op_sel_hi:[1,0,1]
	s_waitcnt lgkmcnt(1)
	v_pk_fma_f32 v[76:77], v[56:57], v[218:219], v[76:77] op_sel_hi:[1,0,1]
	v_pk_fma_f32 v[74:75], v[54:55], v[218:219], v[74:75] op_sel_hi:[1,0,1]
	s_waitcnt lgkmcnt(0)
	v_pk_fma_f32 v[72:73], v[56:57], v[220:221], v[72:73] op_sel_hi:[1,0,1]
	v_pk_fma_f32 v[70:71], v[54:55], v[220:221], v[70:71] op_sel_hi:[1,0,1]
	s_or_b64 exec, exec, s[6:7]
	v_cmp_gt_u32_e64 s[0:1], s18, v131
	s_and_saveexec_b64 s[6:7], s[0:1]
	s_cbranch_execnz .LBB0_1578

.LBB0_1572:
	ds_read_b32 v82, v132 offset:896
	ds_read_b32 v216, v132 offset:5120
	ds_read_b32 v218, v132 offset:9344
	ds_read_b32 v220, v132 offset:13568
	s_waitcnt vmcnt(0) lgkmcnt(3)
	v_pk_fma_f32 v[68:69], v[64:65], v[82:83], v[68:69] op_sel_hi:[1,0,1]
	v_pk_fma_f32 v[66:67], v[62:63], v[82:83], v[66:67] op_sel_hi:[1,0,1]
	s_waitcnt lgkmcnt(2)
	v_pk_fma_f32 v[80:81], v[64:65], v[216:217], v[80:81] op_sel_hi:[1,0,1]
	v_pk_fma_f32 v[78:79], v[62:63], v[216:217], v[78:79] op_sel_hi:[1,0,1]
	s_waitcnt lgkmcnt(1)
	v_pk_fma_f32 v[76:77], v[64:65], v[218:219], v[76:77] op_sel_hi:[1,0,1]
	v_pk_fma_f32 v[74:75], v[62:63], v[218:219], v[74:75] op_sel_hi:[1,0,1]
	s_waitcnt lgkmcnt(0)
	v_pk_fma_f32 v[72:73], v[64:65], v[220:221], v[72:73] op_sel_hi:[1,0,1]
	v_pk_fma_f32 v[70:71], v[62:63], v[220:221], v[70:71] op_sel_hi:[1,0,1]
	s_or_b64 exec, exec, s[6:7]
	s_and_saveexec_b64 s[0:1], vcc
	s_cbranch_execz .LBB0_1562
	s_branch .LBB0_1580

.LBB0_1574:
	ds_read_b32 v82, v132 offset:256
	ds_read_b32 v216, v132 offset:4480
	ds_read_b32 v218, v132 offset:8704
	ds_read_b32 v220, v132 offset:12928
	s_waitcnt vmcnt(5) lgkmcnt(3)
	v_pk_fma_f32 v[68:69], v[44:45], v[82:83], v[68:69] op_sel_hi:[1,0,1]
	v_pk_fma_f32 v[66:67], v[42:43], v[82:83], v[66:67] op_sel_hi:[1,0,1]
	s_waitcnt lgkmcnt(2)
	v_pk_fma_f32 v[80:81], v[44:45], v[216:217], v[80:81] op_sel_hi:[1,0,1]
	v_pk_fma_f32 v[78:79], v[42:43], v[216:217], v[78:79] op_sel_hi:[1,0,1]
	s_waitcnt lgkmcnt(1)
	v_pk_fma_f32 v[76:77], v[44:45], v[218:219], v[76:77] op_sel_hi:[1,0,1]
	v_pk_fma_f32 v[74:75], v[42:43], v[218:219], v[74:75] op_sel_hi:[1,0,1]
	s_waitcnt lgkmcnt(0)
	v_pk_fma_f32 v[72:73], v[44:45], v[220:221], v[72:73] op_sel_hi:[1,0,1]
	v_pk_fma_f32 v[70:71], v[42:43], v[220:221], v[70:71] op_sel_hi:[1,0,1]
	s_or_b64 exec, exec, s[6:7]
	v_cmp_gt_u32_e64 s[0:1], s23, v131
	s_and_saveexec_b64 s[6:7], s[0:1]
	s_cbranch_execnz .LBB0_1568

.LBB0_1576:
	ds_read_b32 v82, v132 offset:512
	ds_read_b32 v216, v132 offset:4736
	ds_read_b32 v218, v132 offset:8960
	ds_read_b32 v220, v132 offset:13184
	s_waitcnt vmcnt(3) lgkmcnt(3)
	v_pk_fma_f32 v[68:69], v[52:53], v[82:83], v[68:69] op_sel_hi:[1,0,1]
	v_pk_fma_f32 v[66:67], v[50:51], v[82:83], v[66:67] op_sel_hi:[1,0,1]
	s_waitcnt lgkmcnt(2)
	v_pk_fma_f32 v[80:81], v[52:53], v[216:217], v[80:81] op_sel_hi:[1,0,1]
	v_pk_fma_f32 v[78:79], v[50:51], v[216:217], v[78:79] op_sel_hi:[1,0,1]
	s_waitcnt lgkmcnt(1)
	v_pk_fma_f32 v[76:77], v[52:53], v[218:219], v[76:77] op_sel_hi:[1,0,1]
	v_pk_fma_f32 v[74:75], v[50:51], v[218:219], v[74:75] op_sel_hi:[1,0,1]
	s_waitcnt lgkmcnt(0)
	v_pk_fma_f32 v[72:73], v[52:53], v[220:221], v[72:73] op_sel_hi:[1,0,1]
	v_pk_fma_f32 v[70:71], v[50:51], v[220:221], v[70:71] op_sel_hi:[1,0,1]
	s_or_b64 exec, exec, s[6:7]
	v_cmp_gt_u32_e64 s[0:1], s17, v131
	s_and_saveexec_b64 s[6:7], s[0:1]
	s_cbranch_execnz .LBB0_1570

.LBB0_1578:
	ds_read_b32 v82, v132 offset:768
	ds_read_b32 v216, v132 offset:4992
	ds_read_b32 v218, v132 offset:9216
	ds_read_b32 v220, v132 offset:13440
	s_waitcnt vmcnt(1) lgkmcnt(3)
	v_pk_fma_f32 v[68:69], v[60:61], v[82:83], v[68:69] op_sel_hi:[1,0,1]
	v_pk_fma_f32 v[66:67], v[58:59], v[82:83], v[66:67] op_sel_hi:[1,0,1]
	s_waitcnt lgkmcnt(2)
	v_pk_fma_f32 v[80:81], v[60:61], v[216:217], v[80:81] op_sel_hi:[1,0,1]
	v_pk_fma_f32 v[78:79], v[58:59], v[216:217], v[78:79] op_sel_hi:[1,0,1]
	s_waitcnt lgkmcnt(1)
	v_pk_fma_f32 v[76:77], v[60:61], v[218:219], v[76:77] op_sel_hi:[1,0,1]
	v_pk_fma_f32 v[74:75], v[58:59], v[218:219], v[74:75] op_sel_hi:[1,0,1]
	s_waitcnt lgkmcnt(0)
	v_pk_fma_f32 v[72:73], v[60:61], v[220:221], v[72:73] op_sel_hi:[1,0,1]
	v_pk_fma_f32 v[70:71], v[58:59], v[220:221], v[70:71] op_sel_hi:[1,0,1]
	s_or_b64 exec, exec, s[6:7]
	v_cmp_gt_u32_e64 s[0:1], s19, v131
	s_and_saveexec_b64 s[6:7], s[0:1]
	s_cbranch_execnz .LBB0_1572

.LBB0_1582:
	s_or_b64 exec, exec, s[6:7]
	ds_read_b32 v82, v132 offset:1024
	v_cmp_gt_u32_e32 vcc, s34, v131
	s_waitcnt vmcnt(7) lgkmcnt(0)
	v_pk_fma_f32 v[68:69], v[4:5], v[82:83], v[68:69] op_sel_hi:[1,0,1]
	v_pk_fma_f32 v[66:67], v[2:3], v[82:83], v[66:67] op_sel_hi:[1,0,1]
	ds_read_b32 v82, v132 offset:5248
	s_waitcnt lgkmcnt(0)
	v_pk_fma_f32 v[80:81], v[4:5], v[82:83], v[80:81] op_sel_hi:[1,0,1]
	v_pk_fma_f32 v[78:79], v[2:3], v[82:83], v[78:79] op_sel_hi:[1,0,1]
	ds_read_b32 v82, v132 offset:9472
	s_waitcnt lgkmcnt(0)
	v_pk_fma_f32 v[76:77], v[4:5], v[82:83], v[76:77] op_sel_hi:[1,0,1]
	v_pk_fma_f32 v[74:75], v[2:3], v[82:83], v[74:75] op_sel_hi:[1,0,1]
	ds_read_b32 v82, v132 offset:13696
	s_waitcnt lgkmcnt(0)
	v_pk_fma_f32 v[72:73], v[4:5], v[82:83], v[72:73] op_sel_hi:[1,0,1]
	v_pk_fma_f32 v[70:71], v[2:3], v[82:83], v[70:71] op_sel_hi:[1,0,1]
	s_and_saveexec_b64 s[6:7], vcc
	s_cbranch_execz .LBB0_1589
	ds_read_b32 v82, v132 offset:1152
	ds_read_b32 v216, v132 offset:5376
	ds_read_b32 v218, v132 offset:9600
	ds_read_b32 v220, v132 offset:13824
	s_waitcnt vmcnt(6) lgkmcnt(3)
	v_pk_fma_f32 v[68:69], v[8:9], v[82:83], v[68:69] op_sel_hi:[1,0,1]
	v_pk_fma_f32 v[66:67], v[6:7], v[82:83], v[66:67] op_sel_hi:[1,0,1]
	s_waitcnt lgkmcnt(2)
	v_pk_fma_f32 v[80:81], v[8:9], v[216:217], v[80:81] op_sel_hi:[1,0,1]
	v_pk_fma_f32 v[78:79], v[6:7], v[216:217], v[78:79] op_sel_hi:[1,0,1]
	s_waitcnt lgkmcnt(1)
	v_pk_fma_f32 v[76:77], v[8:9], v[218:219], v[76:77] op_sel_hi:[1,0,1]
	v_pk_fma_f32 v[74:75], v[6:7], v[218:219], v[74:75] op_sel_hi:[1,0,1]
	s_waitcnt lgkmcnt(0)
	v_pk_fma_f32 v[72:73], v[8:9], v[220:221], v[72:73] op_sel_hi:[1,0,1]
	v_pk_fma_f32 v[70:71], v[6:7], v[220:221], v[70:71] op_sel_hi:[1,0,1]
	s_or_b64 exec, exec, s[6:7]
	v_cmp_gt_u32_e32 vcc, s15, v131
	s_and_saveexec_b64 s[6:7], vcc
	s_cbranch_execnz .LBB0_1590

.LBB0_1585:
	ds_read_b32 v82, v132 offset:1408
	ds_read_b32 v216, v132 offset:5632
	ds_read_b32 v218, v132 offset:9856
	ds_read_b32 v220, v132 offset:14080
	s_waitcnt vmcnt(4) lgkmcnt(3)
	v_pk_fma_f32 v[68:69], v[16:17], v[82:83], v[68:69] op_sel_hi:[1,0,1]
	v_pk_fma_f32 v[66:67], v[14:15], v[82:83], v[66:67] op_sel_hi:[1,0,1]
	s_waitcnt lgkmcnt(2)
	v_pk_fma_f32 v[80:81], v[16:17], v[216:217], v[80:81] op_sel_hi:[1,0,1]
	v_pk_fma_f32 v[78:79], v[14:15], v[216:217], v[78:79] op_sel_hi:[1,0,1]
	s_waitcnt lgkmcnt(1)
	v_pk_fma_f32 v[76:77], v[16:17], v[218:219], v[76:77] op_sel_hi:[1,0,1]
	v_pk_fma_f32 v[74:75], v[14:15], v[218:219], v[74:75] op_sel_hi:[1,0,1]
	s_waitcnt lgkmcnt(0)
	v_pk_fma_f32 v[72:73], v[16:17], v[220:221], v[72:73] op_sel_hi:[1,0,1]
	v_pk_fma_f32 v[70:71], v[14:15], v[220:221], v[70:71] op_sel_hi:[1,0,1]
	s_or_b64 exec, exec, s[6:7]
	v_cmp_gt_u32_e32 vcc, s13, v131
	s_and_saveexec_b64 s[6:7], vcc
	s_cbranch_execnz .LBB0_1592

.LBB0_1587:
	ds_read_b32 v82, v132 offset:1664
	ds_read_b32 v216, v132 offset:5888
	ds_read_b32 v218, v132 offset:10112
	ds_read_b32 v220, v132 offset:14336
	s_waitcnt vmcnt(2) lgkmcnt(3)
	v_pk_fma_f32 v[68:69], v[24:25], v[82:83], v[68:69] op_sel_hi:[1,0,1]
	v_pk_fma_f32 v[66:67], v[22:23], v[82:83], v[66:67] op_sel_hi:[1,0,1]
	s_waitcnt lgkmcnt(2)
	v_pk_fma_f32 v[80:81], v[24:25], v[216:217], v[80:81] op_sel_hi:[1,0,1]
	v_pk_fma_f32 v[78:79], v[22:23], v[216:217], v[78:79] op_sel_hi:[1,0,1]
	s_waitcnt lgkmcnt(1)
	v_pk_fma_f32 v[76:77], v[24:25], v[218:219], v[76:77] op_sel_hi:[1,0,1]
	v_pk_fma_f32 v[74:75], v[22:23], v[218:219], v[74:75] op_sel_hi:[1,0,1]
	s_waitcnt lgkmcnt(0)
	v_pk_fma_f32 v[72:73], v[24:25], v[220:221], v[72:73] op_sel_hi:[1,0,1]
	v_pk_fma_f32 v[70:71], v[22:23], v[220:221], v[70:71] op_sel_hi:[1,0,1]
	s_or_b64 exec, exec, s[6:7]
	v_cmp_gt_u32_e32 vcc, s65, v131
	s_and_saveexec_b64 s[6:7], vcc
	s_cbranch_execnz .LBB0_1594

.LBB0_1590:
	ds_read_b32 v82, v132 offset:1280
	ds_read_b32 v216, v132 offset:5504
	ds_read_b32 v218, v132 offset:9728
	ds_read_b32 v220, v132 offset:13952
	s_waitcnt vmcnt(5) lgkmcnt(3)
	v_pk_fma_f32 v[68:69], v[12:13], v[82:83], v[68:69] op_sel_hi:[1,0,1]
	v_pk_fma_f32 v[66:67], v[10:11], v[82:83], v[66:67] op_sel_hi:[1,0,1]
	s_waitcnt lgkmcnt(2)
	v_pk_fma_f32 v[80:81], v[12:13], v[216:217], v[80:81] op_sel_hi:[1,0,1]
	v_pk_fma_f32 v[78:79], v[10:11], v[216:217], v[78:79] op_sel_hi:[1,0,1]
	s_waitcnt lgkmcnt(1)
	v_pk_fma_f32 v[76:77], v[12:13], v[218:219], v[76:77] op_sel_hi:[1,0,1]
	v_pk_fma_f32 v[74:75], v[10:11], v[218:219], v[74:75] op_sel_hi:[1,0,1]
	s_waitcnt lgkmcnt(0)
	v_pk_fma_f32 v[72:73], v[12:13], v[220:221], v[72:73] op_sel_hi:[1,0,1]
	v_pk_fma_f32 v[70:71], v[10:11], v[220:221], v[70:71] op_sel_hi:[1,0,1]
	s_or_b64 exec, exec, s[6:7]
	v_cmp_gt_u32_e32 vcc, s14, v131
	s_and_saveexec_b64 s[6:7], vcc
	s_cbranch_execnz .LBB0_1585

.LBB0_1592:
	ds_read_b32 v82, v132 offset:1536
	ds_read_b32 v216, v132 offset:5760
	ds_read_b32 v218, v132 offset:9984
	ds_read_b32 v220, v132 offset:14208
	s_waitcnt vmcnt(3) lgkmcnt(3)
	v_pk_fma_f32 v[68:69], v[20:21], v[82:83], v[68:69] op_sel_hi:[1,0,1]
	v_pk_fma_f32 v[66:67], v[18:19], v[82:83], v[66:67] op_sel_hi:[1,0,1]
	s_waitcnt lgkmcnt(2)
	v_pk_fma_f32 v[80:81], v[20:21], v[216:217], v[80:81] op_sel_hi:[1,0,1]
	v_pk_fma_f32 v[78:79], v[18:19], v[216:217], v[78:79] op_sel_hi:[1,0,1]
	s_waitcnt lgkmcnt(1)
	v_pk_fma_f32 v[76:77], v[20:21], v[218:219], v[76:77] op_sel_hi:[1,0,1]
	v_pk_fma_f32 v[74:75], v[18:19], v[218:219], v[74:75] op_sel_hi:[1,0,1]
	s_waitcnt lgkmcnt(0)
	v_pk_fma_f32 v[72:73], v[20:21], v[220:221], v[72:73] op_sel_hi:[1,0,1]
	v_pk_fma_f32 v[70:71], v[18:19], v[220:221], v[70:71] op_sel_hi:[1,0,1]
	s_or_b64 exec, exec, s[6:7]
	v_cmp_gt_u32_e32 vcc, s12, v131
	s_and_saveexec_b64 s[6:7], vcc
	s_cbranch_execnz .LBB0_1587

.LBB0_1594:
	ds_read_b32 v82, v132 offset:1792
	ds_read_b32 v216, v132 offset:6016
	ds_read_b32 v218, v132 offset:10240
	ds_read_b32 v220, v132 offset:14464
	s_waitcnt vmcnt(1) lgkmcnt(3)
	v_pk_fma_f32 v[68:69], v[28:29], v[82:83], v[68:69] op_sel_hi:[1,0,1]
	v_pk_fma_f32 v[66:67], v[26:27], v[82:83], v[66:67] op_sel_hi:[1,0,1]
	s_waitcnt lgkmcnt(2)
	v_pk_fma_f32 v[80:81], v[28:29], v[216:217], v[80:81] op_sel_hi:[1,0,1]
	v_pk_fma_f32 v[78:79], v[26:27], v[216:217], v[78:79] op_sel_hi:[1,0,1]
	s_waitcnt lgkmcnt(1)
	v_pk_fma_f32 v[76:77], v[28:29], v[218:219], v[76:77] op_sel_hi:[1,0,1]
	v_pk_fma_f32 v[74:75], v[26:27], v[218:219], v[74:75] op_sel_hi:[1,0,1]
	s_waitcnt lgkmcnt(0)
	v_pk_fma_f32 v[72:73], v[28:29], v[220:221], v[72:73] op_sel_hi:[1,0,1]
	v_pk_fma_f32 v[70:71], v[26:27], v[220:221], v[70:71] op_sel_hi:[1,0,1]
	s_or_b64 exec, exec, s[6:7]
	v_cmp_gt_u32_e32 vcc, s53, v131
	s_and_saveexec_b64 s[6:7], vcc
	s_cbranch_execz .LBB0_1561
.LBB0_1595:
	ds_read_b32 v82, v132 offset:1920
	ds_read_b32 v216, v132 offset:6144
	ds_read_b32 v218, v132 offset:10368
	ds_read_b32 v220, v132 offset:14592
	s_waitcnt vmcnt(0) lgkmcnt(3)
	v_pk_fma_f32 v[68:69], v[32:33], v[82:83], v[68:69] op_sel_hi:[1,0,1]
	v_pk_fma_f32 v[66:67], v[30:31], v[82:83], v[66:67] op_sel_hi:[1,0,1]
	s_waitcnt lgkmcnt(2)
	v_pk_fma_f32 v[80:81], v[32:33], v[216:217], v[80:81] op_sel_hi:[1,0,1]
	v_pk_fma_f32 v[78:79], v[30:31], v[216:217], v[78:79] op_sel_hi:[1,0,1]
	s_waitcnt lgkmcnt(1)
	v_pk_fma_f32 v[76:77], v[32:33], v[218:219], v[76:77] op_sel_hi:[1,0,1]
	v_pk_fma_f32 v[74:75], v[30:31], v[218:219], v[74:75] op_sel_hi:[1,0,1]
	s_waitcnt lgkmcnt(0)
	v_pk_fma_f32 v[72:73], v[32:33], v[220:221], v[72:73] op_sel_hi:[1,0,1]
	v_pk_fma_f32 v[70:71], v[30:31], v[220:221], v[70:71] op_sel_hi:[1,0,1]
	s_branch .LBB0_1561
